# adds: the q/k chunk-tile LDS-DMA loads of the GLA scan are issued by the (slack) consumer waves at the top of their step instead of by the producer waves
# baseline (speedup 1.0000x reference)
; __device__ __forceinline__ void gla_scan_phase2(LAS unsigned char* lds, const bf16_t* proj, const float* gbuf, const float* wgu  , const float* bg  ,
;                                                 bf16_t* ob0, bf16_t* ob1) {
;     ...
;                     unsigned short qv[16], kv[16];
; #pragma unroll
;                     for (int ii = 0; ii < 16; ++ii) { qv[ii] = __builtin_amdgcn_raw_buffer_load_b16(prs, qvoff, srow + (unsigned)(ii * GINP * 2), 0);
;                                                        kv[ii] = __builtin_amdgcn_raw_buffer_load_b16(prs, qvoff + 1024u, srow + (unsigned)(ii * GINP * 2), 0); }
;     ...
;             const int cw = wave - 4;
;             bf16_t* ob = dir ? ob1 : ob0;
;             const __amdgpu_buffer_rsrc_t ors = __builtin_amdgcn_make_buffer_rsrc((void*)ob, 0, (unsigned)((size_t)MTOK * DM * 2), 0x00020000);
;             const unsigned ovoff = (unsigned)((r * DM + h * 256 + 64 * cw + 4 * hh) * 2);
;             f32x16 S[2][4];
; #pragma unroll
;             for (int nt2 = 0; nt2 < 2; ++nt2)
; #pragma unroll
;                 for (int kt = 0; kt < 4; ++kt)
; #pragma unroll
;                     for (int i = 0; i < 16; ++i) S[nt2][kt][i] = 0.f;
;             for (int n = 0; n <= NCH; ++n) {
;                 if (n >= 1) {
;                     const int mch = n - 1;
;                     const int tok0 = b * SEQ + (dir ? NCH - 1 - mch : mch) * CH;
.LBB0_213:
	s_ashr_i32 s9, s14, 3
	s_bfe_u32 s15, s14, 0x20001
	s_and_b32 s8, s14, 1
	s_mov_b64 s[6:7], -1
	s_and_b64 vcc, exec, s[12:13]
	s_cbranch_vccz .LBB0_217
	s_cmp_eq_u32 s8, 0
	s_cselect_b64 s[48:49], -1, 0
	v_and_b32_e32 v214, 15, v179
	v_lshlrev_b32_e32 v214, 4, v214
	v_bfe_u32 v215, v179, 4, 2
	v_bfe_u32 v216, v179, 6, 2
	v_lshl_add_u32 v215, v216, 3, v215
	v_mul_u32_u24_e32 v215, 0x1a00, v215
	v_add_u32_e32 v214, v214, v215
	s_lshl_b32 s26, s15, 8
	v_add_u32_e32 v214, s26, v214
	v_lshlrev_b32_e32 v215, 11, v216
	v_add_u32_e32 v215, 0x1b600, v215
	s_waitcnt lgkmcnt(0)
	s_barrier
	s_and_b64 s[20:21], s[48:49], exec
	s_waitcnt lgkmcnt(0)
	s_barrier
	v_readlane_b32 s20, v253, 23
	s_waitcnt lgkmcnt(0)
	s_barrier
	v_readlane_b32 s21, v253, 24
	s_waitcnt lgkmcnt(0)
	s_barrier
	s_cselect_b32 s0, s73, s21
	v_lshl_add_u32 v160, s15, 9, v212
	v_mov_b32_e32 v0, 0
	s_mov_b32 s6, 0
	s_cselect_b32 s68, s72, s20
	s_and_b32 s69, s0, 0xffff
	s_lshl_b32 s7, s9, 22
	v_or_b32_e32 v193, 16, v160
	v_or_b32_e32 v234, 32, v160
	v_or_b32_e32 v235, 48, v160
	v_or_b32_e32 v236, 64, v160
	v_or_b32_e32 v237, 0x50, v160
	v_or_b32_e32 v238, 0x60, v160
	v_or_b32_e32 v239, 0x70, v160
	s_mov_b32 s20, 63
	v_mov_b32_e32 v1, v0
	v_mov_b32_e32 v2, v0
	v_mov_b32_e32 v3, v0
	v_mov_b32_e32 v4, v0
	v_mov_b32_e32 v5, v0
	v_mov_b32_e32 v6, v0
	v_mov_b32_e32 v7, v0
	v_mov_b32_e32 v8, v0
	v_mov_b32_e32 v9, v0
	v_mov_b32_e32 v10, v0
	v_mov_b32_e32 v11, v0
	v_mov_b32_e32 v12, v0
	v_mov_b32_e32 v13, v0
	v_mov_b32_e32 v14, v0
	v_mov_b32_e32 v15, v0
	v_mov_b32_e32 v16, v0
	v_mov_b32_e32 v17, v0
	v_mov_b32_e32 v18, v0
	v_mov_b32_e32 v19, v0
	v_mov_b32_e32 v20, v0
	v_mov_b32_e32 v21, v0
	v_mov_b32_e32 v22, v0
	v_mov_b32_e32 v23, v0
	v_mov_b32_e32 v24, v0
	v_mov_b32_e32 v25, v0
	v_mov_b32_e32 v26, v0
	v_mov_b32_e32 v27, v0
	v_mov_b32_e32 v28, v0
	v_mov_b32_e32 v29, v0
	v_mov_b32_e32 v30, v0
	v_mov_b32_e32 v31, v0
	v_mov_b32_e32 v32, v0
	v_mov_b32_e32 v33, v0
	v_mov_b32_e32 v34, v0
	v_mov_b32_e32 v35, v0
	v_mov_b32_e32 v36, v0
	v_mov_b32_e32 v37, v0
	v_mov_b32_e32 v38, v0
	v_mov_b32_e32 v39, v0
	s_waitcnt vmcnt(1)
	v_mov_b32_e32 v40, v0
	v_mov_b32_e32 v41, v0
	v_mov_b32_e32 v42, v0
	v_mov_b32_e32 v43, v0
	s_waitcnt vmcnt(0)
	v_mov_b32_e32 v44, v0
	v_mov_b32_e32 v45, v0
	v_mov_b32_e32 v46, v0
	v_mov_b32_e32 v47, v0
	v_mov_b32_e32 v48, v0
	v_mov_b32_e32 v49, v0
	v_mov_b32_e32 v50, v0
	v_mov_b32_e32 v51, v0
	v_mov_b32_e32 v52, v0
	v_mov_b32_e32 v53, v0
	v_mov_b32_e32 v54, v0
	v_mov_b32_e32 v55, v0
	v_mov_b32_e32 v56, v0
	v_mov_b32_e32 v57, v0
	v_mov_b32_e32 v58, v0
	v_mov_b32_e32 v59, v0
	v_mov_b32_e32 v60, v0
	v_mov_b32_e32 v61, v0
	v_mov_b32_e32 v62, v0
	v_mov_b32_e32 v63, v0
	v_mov_b32_e32 v64, v0
	v_mov_b32_e32 v65, v0
	v_mov_b32_e32 v66, v0
	v_mov_b32_e32 v67, v0
	v_mov_b32_e32 v68, v0
	v_mov_b32_e32 v69, v0
	v_mov_b32_e32 v70, v0
	v_mov_b32_e32 v71, v0
	v_mov_b32_e32 v72, v0
	v_mov_b32_e32 v73, v0
	v_mov_b32_e32 v74, v0
	v_mov_b32_e32 v75, v0
	v_mov_b32_e32 v76, v0
	v_mov_b32_e32 v77, v0
	v_mov_b32_e32 v78, v0
	v_mov_b32_e32 v79, v0
	v_mov_b32_e32 v80, v0
	v_mov_b32_e32 v81, v0
	v_mov_b32_e32 v82, v0
	v_mov_b32_e32 v83, v0
	v_mov_b32_e32 v84, v0
	v_mov_b32_e32 v85, v0
	v_mov_b32_e32 v86, v0
	v_mov_b32_e32 v87, v0
	v_mov_b32_e32 v88, v0
	v_mov_b32_e32 v89, v0
	v_mov_b32_e32 v90, v0
	v_mov_b32_e32 v91, v0
	v_mov_b32_e32 v92, v0
	v_mov_b32_e32 v93, v0
	v_mov_b32_e32 v94, v0
	v_mov_b32_e32 v95, v0
	v_mov_b32_e32 v96, v0
	v_mov_b32_e32 v97, v0
	v_mov_b32_e32 v98, v0
	v_mov_b32_e32 v99, v0
	v_mov_b32_e32 v100, v0
	v_mov_b32_e32 v101, v0
	v_mov_b32_e32 v102, v0
	v_mov_b32_e32 v103, v0
	v_mov_b32_e32 v104, v0
	v_mov_b32_e32 v105, v0
	v_mov_b32_e32 v106, v0
	v_mov_b32_e32 v107, v0
	v_mov_b32_e32 v108, v0
	v_mov_b32_e32 v109, v0
	v_mov_b32_e32 v110, v0
	v_mov_b32_e32 v111, v0
	v_mov_b32_e32 v112, v0
	v_mov_b32_e32 v113, v0
	v_mov_b32_e32 v114, v0
	v_mov_b32_e32 v115, v0
	v_mov_b32_e32 v116, v0
	v_mov_b32_e32 v117, v0
	v_mov_b32_e32 v118, v0
	v_mov_b32_e32 v119, v0
	v_mov_b32_e32 v120, v0
	v_mov_b32_e32 v121, v0
	v_mov_b32_e32 v122, v0
	v_mov_b32_e32 v123, v0
	v_mov_b32_e32 v124, v0
	v_mov_b32_e32 v125, v0
	v_mov_b32_e32 v126, v0
	v_mov_b32_e32 v127, v0
.LBB0_215:
	s_cmp_eq_u32 s6, 63
	s_cbranch_scc1 .Lc_dma_skip
	s_and_b64 s[24:25], s[48:49], exec
	s_cselect_b32 s26, s6, s20
	s_cselect_b32 s28, 1, -1
	s_add_i32 s26, s26, s28
	s_lshl_b32 s26, s26, 5
	s_lshl_b32 s28, s9, 11
	s_add_i32 s26, s26, s28
	s_mulk_i32 s26, 0x1a00
	s_add_u32 s78, s64, s26
	s_addc_u32 s79, s65, 0
	s_add_u32 s80, s78, 0x6800
	s_addc_u32 s81, s79, 0
	s_add_u32 s82, s78, 0x400
	s_addc_u32 s83, s79, 0
	v_readfirstlane_b32 s26, v215
	s_nop 3
	s_mov_b32 m0, s26
	s_nop 0
	global_load_lds_dwordx4 v214, s[78:79]
	s_add_i32 m0, s26, 0x400
	s_nop 0
	global_load_lds_dwordx4 v214, s[80:81]
	s_add_i32 m0, s26, 0x2000
	s_nop 0
	global_load_lds_dwordx4 v214, s[82:83]
	s_add_u32 s82, s80, 0x400
	s_addc_u32 s83, s81, 0
	s_add_i32 m0, s26, 0x2400
	s_nop 0
	global_load_lds_dwordx4 v214, s[82:83]
; #define LAS __attribute__((address_space(3)))
; __device__ __forceinline__ unsigned pk2(float lo, float hi) { f32x2 v = {lo, hi}; bf16x2_t b = __builtin_convertvector(v, bf16x2_t); return __builtin_bit_cast(unsigned, b); }
; #define MFMA32(a, b, c) __builtin_amdgcn_mfma_f32_32x32x16_bf16((a), (b), (c), 0, 0, 0)
; #define G2_BAR() do { asm volatile("s_waitcnt lgkmcnt(0)" ::: "memory"); __builtin_amdgcn_s_barrier(); asm volatile("" ::: "memory"); } while (0)
; __device__ __forceinline__ void gla_scan_phase2(LAS unsigned char* lds, const bf16_t* proj, const float* gbuf, const float* wgu  , const float* bg  ,
;                                                 bf16_t* ob0, bf16_t* ob1) {
;     ...
;                     bf16x8 bv[2][2];
; #pragma unroll
;                     for (int nt2 = 0; nt2 < 2; ++nt2)
; #pragma unroll
;                         for (int ks = 0; ks < 2; ++ks) bv[nt2][ks] = *(const LAS bf16x8*)(set + G2_VT + (64 * cw + 32 * nt2 + r) * 80 + ks * 32 + hh * 16);
;                     f32x16 oacc[2];
; #pragma unroll
;                     for (int nt2 = 0; nt2 < 2; ++nt2)
; #pragma unroll
;                         for (int i = 0; i < 16; ++i) oacc[nt2][i] = 0.f;
; #pragma unroll
;                     for (int ks = 0; ks < 2; ++ks) {
;                         const bf16x8 a = *(const LAS bf16x8*)(set + G2_SC + r * 80 + ks * 32 + hh * 16);
; #pragma unroll
;                         for (int nt2 = 0; nt2 < 2; ++nt2) oacc[nt2] = MFMA32(bv[nt2][ks], a, oacc[nt2]);
;                     }
;     ...
;                     G2_OINTER(0);
;                     G2_BAR();
;                     G2_OINTER(1); G2_OINTER(2);
;                     G2_BAR();
;                     G2_OINTER(3);
;                     {
;                         const unsigned orow = (unsigned)tok0 * (unsigned)(DM * 2);
; #pragma unroll
;                         for (int nt2 = 0; nt2 < 2; ++nt2)
; #pragma unroll
;                             for (int g = 0; g < 4; ++g) {
;                                 u32x2 w; w.x = pk2(oacc[nt2][4 * g], oacc[nt2][4 * g + 1]); w.y = pk2(oacc[nt2][4 * g + 2], oacc[nt2][4 * g + 3]);
;                                 __builtin_amdgcn_raw_buffer_store_b64(w, ors, ovoff + (unsigned)((32 * nt2 + 8 * g) * 2), orow, 0);
;                             }
;                     }
.Lc_dma_skip:
	s_and_b64 s[24:25], s[48:49], exec
	s_cselect_b32 s21, s6, s20
	s_bitcmp1_b32 s6, 0
	s_cselect_b32 s0, 0xa800, 0
	s_add_i32 s0, s0, 0
	v_add_u32_e32 v241, s0, v195
	v_add_u32_e32 v166, v241, v210
	ds_read_b128 v[170:173], v166 offset:18944
	ds_read_b128 v[174:177], v166 offset:21504
	v_add_u32_e32 v240, v241, v196
	ds_read_b128 v[128:131], v240 offset:39424
	ds_read_b128 v[162:165], v166 offset:18976
	ds_read_b128 v[242:245], v240 offset:39456
	ds_read_b128 v[166:169], v166 offset:21536
	v_add3_u32 v250, s0, v197, v188
	s_waitcnt lgkmcnt(3)
	v_mfma_f32_32x32x16_bf16 v[144:159], v[170:173], v[128:131], 0
	v_mfma_f32_32x32x16_bf16 v[128:143], v[174:177], v[128:131], 0
	s_waitcnt lgkmcnt(1)
	v_mfma_f32_32x32x16_bf16 v[144:159], v[162:165], v[242:245], v[144:159]
	s_waitcnt lgkmcnt(0)
	v_mfma_f32_32x32x16_bf16 v[128:143], v[166:169], v[242:245], v[128:143]
	ds_read2_b64 v[242:245], v250 offset1:2
	v_cvt_pk_bf16_f32 v246, v112, v113
	v_cvt_pk_bf16_f32 v247, v114, v115
	v_cvt_pk_bf16_f32 v248, v116, v117
	v_cvt_pk_bf16_f32 v249, v118, v119
	s_waitcnt lgkmcnt(0)
	s_nop 0
	v_mfma_f32_32x32x16_bf16 v[144:159], v[246:249], v[242:245], v[144:159]
	v_cvt_pk_bf16_f32 v246, v48, v49
	v_cvt_pk_bf16_f32 v247, v50, v51
	v_cvt_pk_bf16_f32 v248, v52, v53
	v_cvt_pk_bf16_f32 v249, v54, v55
	s_nop 1
	v_mfma_f32_32x32x16_bf16 v[128:143], v[246:249], v[242:245], v[128:143]
	ds_read2_b64 v[242:245], v250 offset0:4 offset1:6
	v_cvt_pk_bf16_f32 v246, v120, v121
	v_cvt_pk_bf16_f32 v247, v122, v123
	v_cvt_pk_bf16_f32 v248, v124, v125
	v_cvt_pk_bf16_f32 v249, v126, v127
	s_waitcnt lgkmcnt(0)
	s_barrier
	s_waitcnt lgkmcnt(0)
	v_mfma_f32_32x32x16_bf16 v[144:159], v[246:249], v[242:245], v[144:159]
	v_cvt_pk_bf16_f32 v246, v56, v57
	v_cvt_pk_bf16_f32 v247, v58, v59
	v_cvt_pk_bf16_f32 v248, v60, v61
	v_cvt_pk_bf16_f32 v249, v62, v63
	s_nop 1
	v_mfma_f32_32x32x16_bf16 v[128:143], v[246:249], v[242:245], v[128:143]
	ds_read2_b64 v[242:245], v250 offset0:8 offset1:10
	v_cvt_pk_bf16_f32 v246, v96, v97
	v_cvt_pk_bf16_f32 v247, v98, v99
	v_cvt_pk_bf16_f32 v248, v100, v101
	v_cvt_pk_bf16_f32 v249, v102, v103
	s_waitcnt lgkmcnt(0)
	s_nop 0
	v_mfma_f32_32x32x16_bf16 v[144:159], v[246:249], v[242:245], v[144:159]
	v_cvt_pk_bf16_f32 v246, v32, v33
	v_cvt_pk_bf16_f32 v247, v34, v35
	v_cvt_pk_bf16_f32 v248, v36, v37
	v_cvt_pk_bf16_f32 v249, v38, v39
	s_nop 1
	v_mfma_f32_32x32x16_bf16 v[128:143], v[246:249], v[242:245], v[128:143]
	ds_read2_b64 v[242:245], v250 offset0:12 offset1:14
	v_cvt_pk_bf16_f32 v246, v104, v105
	v_cvt_pk_bf16_f32 v247, v106, v107
	v_cvt_pk_bf16_f32 v248, v108, v109
	v_cvt_pk_bf16_f32 v249, v110, v111
	s_waitcnt lgkmcnt(0)
	s_nop 0
	v_mfma_f32_32x32x16_bf16 v[144:159], v[246:249], v[242:245], v[144:159]
	v_cvt_pk_bf16_f32 v246, v40, v41
	v_cvt_pk_bf16_f32 v247, v42, v43
	v_cvt_pk_bf16_f32 v248, v44, v45
	v_cvt_pk_bf16_f32 v249, v46, v47
	s_nop 1
	v_mfma_f32_32x32x16_bf16 v[128:143], v[246:249], v[242:245], v[128:143]
	ds_read2_b64 v[242:245], v250 offset0:16 offset1:18
	v_cvt_pk_bf16_f32 v246, v80, v81
	v_cvt_pk_bf16_f32 v247, v82, v83
	v_cvt_pk_bf16_f32 v248, v84, v85
	v_cvt_pk_bf16_f32 v249, v86, v87
	s_waitcnt lgkmcnt(0)
	s_nop 0
	v_mfma_f32_32x32x16_bf16 v[144:159], v[246:249], v[242:245], v[144:159]
	v_cvt_pk_bf16_f32 v246, v16, v17
	v_cvt_pk_bf16_f32 v247, v18, v19
	v_cvt_pk_bf16_f32 v248, v20, v21
	v_cvt_pk_bf16_f32 v249, v22, v23
	s_nop 1
	v_mfma_f32_32x32x16_bf16 v[128:143], v[246:249], v[242:245], v[128:143]
	ds_read2_b64 v[242:245], v250 offset0:20 offset1:22
	v_cvt_pk_bf16_f32 v246, v88, v89
	v_cvt_pk_bf16_f32 v247, v90, v91
	v_cvt_pk_bf16_f32 v248, v92, v93
	v_cvt_pk_bf16_f32 v249, v94, v95
	s_waitcnt vmcnt(0)
	s_waitcnt lgkmcnt(0)
	s_barrier
	s_waitcnt lgkmcnt(0)
	v_mfma_f32_32x32x16_bf16 v[144:159], v[246:249], v[242:245], v[144:159]
	v_cvt_pk_bf16_f32 v246, v24, v25
	v_cvt_pk_bf16_f32 v247, v26, v27
	v_cvt_pk_bf16_f32 v248, v28, v29
	v_cvt_pk_bf16_f32 v249, v30, v31
	s_nop 1
	v_mfma_f32_32x32x16_bf16 v[128:143], v[246:249], v[242:245], v[128:143]
	ds_read2_b64 v[242:245], v250 offset0:24 offset1:26
	v_cvt_pk_bf16_f32 v246, v64, v65
	v_cvt_pk_bf16_f32 v247, v66, v67
	v_cvt_pk_bf16_f32 v248, v68, v69
	v_cvt_pk_bf16_f32 v249, v70, v71
	s_waitcnt lgkmcnt(0)
	s_nop 0
	v_mfma_f32_32x32x16_bf16 v[144:159], v[246:249], v[242:245], v[144:159]
	v_cvt_pk_bf16_f32 v246, v0, v1
	v_cvt_pk_bf16_f32 v247, v2, v3
	v_cvt_pk_bf16_f32 v248, v4, v5
	v_cvt_pk_bf16_f32 v249, v6, v7
	s_nop 1
	v_mfma_f32_32x32x16_bf16 v[128:143], v[246:249], v[242:245], v[128:143]
	ds_read2_b64 v[242:245], v250 offset0:28 offset1:30
	v_cvt_pk_bf16_f32 v246, v72, v73
	v_cvt_pk_bf16_f32 v247, v74, v75
	v_cvt_pk_bf16_f32 v248, v76, v77
	v_cvt_pk_bf16_f32 v249, v78, v79
	s_lshl_b32 s0, s21, 16
	s_add_i32 s0, s0, s7
	s_waitcnt lgkmcnt(0)
	v_mfma_f32_32x32x16_bf16 v[144:159], v[246:249], v[242:245], v[144:159]
	v_cvt_pk_bf16_f32 v246, v8, v9
	v_cvt_pk_bf16_f32 v247, v10, v11
	v_cvt_pk_bf16_f32 v248, v12, v13
	v_cvt_pk_bf16_f32 v249, v14, v15
	s_add_i32 s6, s6, 1
	s_add_i32 s20, s20, -1
	s_cmp_eq_u32 s6, 64
	v_mfma_f32_32x32x16_bf16 v[128:143], v[246:249], v[242:245], v[128:143]
	s_nop 3
	v_cvt_pk_bf16_f32 v144, v144, v145
	v_cvt_pk_bf16_f32 v145, v146, v147
	buffer_store_dwordx2 v[144:145], v160, s[68:71], s0 offen
	v_cvt_pk_bf16_f32 v144, v148, v149
	v_cvt_pk_bf16_f32 v145, v150, v151
	buffer_store_dwordx2 v[144:145], v193, s[68:71], s0 offen
	v_cvt_pk_bf16_f32 v144, v152, v153
	v_cvt_pk_bf16_f32 v145, v154, v155
	buffer_store_dwordx2 v[144:145], v234, s[68:71], s0 offen
	v_cvt_pk_bf16_f32 v144, v156, v157
	v_cvt_pk_bf16_f32 v145, v158, v159
	v_cvt_pk_bf16_f32 v128, v128, v129
	v_cvt_pk_bf16_f32 v129, v130, v131
	buffer_store_dwordx2 v[144:145], v235, s[68:71], s0 offen
	buffer_store_dwordx2 v[128:129], v236, s[68:71], s0 offen
	v_cvt_pk_bf16_f32 v128, v132, v133
	v_cvt_pk_bf16_f32 v129, v134, v135
	buffer_store_dwordx2 v[128:129], v237, s[68:71], s0 offen
	v_cvt_pk_bf16_f32 v128, v136, v137
	v_cvt_pk_bf16_f32 v129, v138, v139
	buffer_store_dwordx2 v[128:129], v238, s[68:71], s0 offen
	v_cvt_pk_bf16_f32 v128, v140, v141
	v_cvt_pk_bf16_f32 v129, v142, v143
	buffer_store_dwordx2 v[128:129], v239, s[68:71], s0 offen
	ds_read_b128 v[128:131], v241 offset:41984
	ds_read_b128 v[132:135], v241 offset:42016
	ds_read_b128 v[136:139], v241 offset:42048
	ds_read_b128 v[140:143], v241 offset:42080
	s_waitcnt lgkmcnt(3)
; #define G2_BAR() do { asm volatile("s_waitcnt lgkmcnt(0)" ::: "memory"); __builtin_amdgcn_s_barrier(); asm volatile("" ::: "memory"); } while (0)
; __device__ __forceinline__ void gla_scan_phase2(LAS unsigned char* lds, const bf16_t* proj, const float* gbuf, const float* wgu  , const float* bg  ,
;                                                 bf16_t* ob0, bf16_t* ob1) {
;     ...
;                     G2_STATE(0); G2_STATE(1);
;                     G2_BAR();
;                     G2_STATE(2); G2_STATE(3);
;     ...
;                     G2_BAR();
	v_pk_mul_f32 v[114:115], v[114:115], v[130:131]
	s_waitcnt lgkmcnt(2)
	v_pk_mul_f32 v[118:119], v[118:119], v[134:135]
	v_pk_mul_f32 v[116:117], v[116:117], v[132:133]
	v_pk_mul_f32 v[112:113], v[112:113], v[128:129]
	v_pk_mul_f32 v[54:55], v[54:55], v[134:135]
	v_pk_mul_f32 v[50:51], v[50:51], v[130:131]
	v_pk_mul_f32 v[52:53], v[52:53], v[132:133]
	v_pk_mul_f32 v[48:49], v[48:49], v[128:129]
	ds_read_b128 v[128:131], v240 offset:8704
	ds_read_b128 v[132:135], v240 offset:8736
	s_waitcnt lgkmcnt(2)
	v_pk_mul_f32 v[126:127], v[126:127], v[142:143]
	v_pk_mul_f32 v[122:123], v[122:123], v[138:139]
	v_pk_mul_f32 v[124:125], v[124:125], v[140:141]
	v_pk_mul_f32 v[120:121], v[120:121], v[136:137]
	v_pk_mul_f32 v[62:63], v[62:63], v[142:143]
	v_pk_mul_f32 v[58:59], v[58:59], v[138:139]
	v_pk_mul_f32 v[60:61], v[60:61], v[140:141]
	v_pk_mul_f32 v[56:57], v[56:57], v[136:137]
	s_waitcnt lgkmcnt(1)
	v_mfma_f32_32x32x16_bf16 v[112:127], v[128:131], v[170:173], v[112:127]
	v_mfma_f32_32x32x16_bf16 v[48:63], v[128:131], v[174:177], v[48:63]
	s_waitcnt lgkmcnt(0)
	v_mfma_f32_32x32x16_bf16 v[112:127], v[132:135], v[162:165], v[112:127]
	v_mfma_f32_32x32x16_bf16 v[48:63], v[132:135], v[166:169], v[48:63]
	ds_read_b128 v[128:131], v241 offset:42112
	ds_read_b128 v[132:135], v241 offset:42144
	ds_read_b128 v[136:139], v241 offset:42176
	ds_read_b128 v[140:143], v241 offset:42208
	s_waitcnt lgkmcnt(3)
	v_pk_mul_f32 v[98:99], v[98:99], v[130:131]
	v_pk_mul_f32 v[96:97], v[96:97], v[128:129]
	v_pk_mul_f32 v[34:35], v[34:35], v[130:131]
	v_pk_mul_f32 v[32:33], v[32:33], v[128:129]
	ds_read_b128 v[128:131], v240 offset:11264
	s_waitcnt lgkmcnt(1)
	v_pk_mul_f32 v[110:111], v[110:111], v[142:143]
	v_pk_mul_f32 v[106:107], v[106:107], v[138:139]
	v_pk_mul_f32 v[102:103], v[102:103], v[134:135]
	v_pk_mul_f32 v[108:109], v[108:109], v[140:141]
	v_pk_mul_f32 v[104:105], v[104:105], v[136:137]
	v_pk_mul_f32 v[100:101], v[100:101], v[132:133]
	v_pk_mul_f32 v[46:47], v[46:47], v[142:143]
	v_pk_mul_f32 v[42:43], v[42:43], v[138:139]
	v_pk_mul_f32 v[38:39], v[38:39], v[134:135]
	v_pk_mul_f32 v[44:45], v[44:45], v[140:141]
	v_pk_mul_f32 v[40:41], v[40:41], v[136:137]
	v_pk_mul_f32 v[36:37], v[36:37], v[132:133]
	s_waitcnt lgkmcnt(0)
	v_mfma_f32_32x32x16_bf16 v[96:111], v[128:131], v[170:173], v[96:111]
	v_mfma_f32_32x32x16_bf16 v[32:47], v[128:131], v[174:177], v[32:47]
	ds_read_b128 v[128:131], v240 offset:11296
	s_waitcnt lgkmcnt(0)
	s_barrier
	s_waitcnt lgkmcnt(0)
	v_mfma_f32_32x32x16_bf16 v[96:111], v[128:131], v[162:165], v[96:111]
	v_mfma_f32_32x32x16_bf16 v[32:47], v[128:131], v[166:169], v[32:47]
	ds_read_b128 v[128:131], v241 offset:42240
	ds_read_b128 v[132:135], v241 offset:42272
	ds_read_b128 v[136:139], v241 offset:42304
	ds_read_b128 v[140:143], v241 offset:42336
	s_waitcnt lgkmcnt(3)
	v_pk_mul_f32 v[82:83], v[82:83], v[130:131]
	s_waitcnt lgkmcnt(2)
	v_pk_mul_f32 v[86:87], v[86:87], v[134:135]
	v_pk_mul_f32 v[84:85], v[84:85], v[132:133]
	v_pk_mul_f32 v[80:81], v[80:81], v[128:129]
	v_pk_mul_f32 v[22:23], v[22:23], v[134:135]
	v_pk_mul_f32 v[18:19], v[18:19], v[130:131]
	v_pk_mul_f32 v[20:21], v[20:21], v[132:133]
	v_pk_mul_f32 v[16:17], v[16:17], v[128:129]
	ds_read_b128 v[128:131], v240 offset:13824
	ds_read_b128 v[132:135], v240 offset:13856
	s_waitcnt lgkmcnt(2)
	v_pk_mul_f32 v[94:95], v[94:95], v[142:143]
	v_pk_mul_f32 v[90:91], v[90:91], v[138:139]
	v_pk_mul_f32 v[92:93], v[92:93], v[140:141]
	v_pk_mul_f32 v[88:89], v[88:89], v[136:137]
	v_pk_mul_f32 v[30:31], v[30:31], v[142:143]
	v_pk_mul_f32 v[26:27], v[26:27], v[138:139]
	v_pk_mul_f32 v[28:29], v[28:29], v[140:141]
	v_pk_mul_f32 v[24:25], v[24:25], v[136:137]
	s_waitcnt lgkmcnt(1)
	v_mfma_f32_32x32x16_bf16 v[80:95], v[128:131], v[170:173], v[80:95]
	v_mfma_f32_32x32x16_bf16 v[16:31], v[128:131], v[174:177], v[16:31]
	s_waitcnt lgkmcnt(0)
	v_mfma_f32_32x32x16_bf16 v[80:95], v[132:135], v[162:165], v[80:95]
	v_mfma_f32_32x32x16_bf16 v[16:31], v[132:135], v[166:169], v[16:31]
	ds_read_b128 v[128:131], v241 offset:42368
	ds_read_b128 v[132:135], v241 offset:42400
	ds_read_b128 v[136:139], v241 offset:42432
	ds_read_b128 v[140:143], v241 offset:42464
	s_waitcnt lgkmcnt(3)
	v_pk_mul_f32 v[66:67], v[66:67], v[130:131]
	v_pk_mul_f32 v[64:65], v[64:65], v[128:129]
	v_pk_mul_f32 v[2:3], v[2:3], v[130:131]
	v_pk_mul_f32 v[0:1], v[0:1], v[128:129]
	ds_read_b128 v[128:131], v240 offset:16384
	s_waitcnt lgkmcnt(1)
	v_pk_mul_f32 v[78:79], v[78:79], v[142:143]
	v_pk_mul_f32 v[74:75], v[74:75], v[138:139]
	v_pk_mul_f32 v[70:71], v[70:71], v[134:135]
	v_pk_mul_f32 v[76:77], v[76:77], v[140:141]
	v_pk_mul_f32 v[72:73], v[72:73], v[136:137]
	v_pk_mul_f32 v[68:69], v[68:69], v[132:133]
	v_pk_mul_f32 v[14:15], v[14:15], v[142:143]
	v_pk_mul_f32 v[10:11], v[10:11], v[138:139]
	v_pk_mul_f32 v[6:7], v[6:7], v[134:135]
	v_pk_mul_f32 v[12:13], v[12:13], v[140:141]
	v_pk_mul_f32 v[8:9], v[8:9], v[136:137]
	v_pk_mul_f32 v[4:5], v[4:5], v[132:133]
	s_waitcnt lgkmcnt(0)
	v_mfma_f32_32x32x16_bf16 v[64:79], v[128:131], v[170:173], v[64:79]
	v_mfma_f32_32x32x16_bf16 v[0:15], v[128:131], v[174:177], v[0:15]
	ds_read_b128 v[128:131], v240 offset:16416
	s_waitcnt lgkmcnt(0)
	s_barrier
	s_waitcnt lgkmcnt(0)
	v_mfma_f32_32x32x16_bf16 v[64:79], v[128:131], v[162:165], v[64:79]
	v_mfma_f32_32x32x16_bf16 v[0:15], v[128:131], v[166:169], v[0:15]
	s_cbranch_scc0 .LBB0_215
	s_mov_b64 s[6:7], 0

; #define LAS __attribute__((address_space(3)))
; __device__ __forceinline__ unsigned pk2(float lo, float hi) { f32x2 v = {lo, hi}; bf16x2_t b = __builtin_convertvector(v, bf16x2_t); return __builtin_bit_cast(unsigned, b); }
; #define MFMA16(a, b, c) __builtin_amdgcn_mfma_f32_16x16x32_bf16((a), (b), (c), 0, 0, 0)
; __device__ __forceinline__ void gla_scan_phase2(LAS unsigned char* lds, const bf16_t* proj, const float* gbuf, const float* wgu  , const float* bg  ,
;                                                 bf16_t* ob0, bf16_t* ob1) {
;     ...
;                         unsigned c0[8], c1[8];
; #pragma unroll
;                         for (int t = 0; t < 8; ++t) { const unsigned a_ = vw[2 * t], b_ = vw[2 * t + 1]; c0[t] = (a_ & 0xffffu) | (b_ << 16); c1[t] = (a_ >> 16) | (b_ & 0xffff0000u); }
;                         *(LAS u32x4*)(set + G2_VT + (2 * d) * 80 + seg * 32) = (u32x4){c0[0], c0[1], c0[2], c0[3]};
;                         *(LAS u32x4*)(set + G2_VT + (2 * d) * 80 + seg * 32 + 16) = (u32x4){c0[4], c0[5], c0[6], c0[7]};
;                         *(LAS u32x4*)(set + G2_VT + (2 * d + 1) * 80 + seg * 32) = (u32x4){c1[0], c1[1], c1[2], c1[3]};
;                         *(LAS u32x4*)(set + G2_VT + (2 * d + 1) * 80 + seg * 32 + 16) = (u32x4){c1[4], c1[5], c1[6], c1[7]};
;                     }
;                     G2_BAR();
;                     {
;                         const int ti = wave >> 1, tj = wave & 1;
;                         f32x4 a4 = (f32x4){0.f, 0.f, 0.f, 0.f};
; #pragma unroll
;                         for (int ks = 0; ks < 4; ++ks) {
;                             const bf16x8 ka = *(const LAS bf16x8*)(lds + G2_KI + (16 * tj + fr) * 272 + ks * 64 + fq * 16);
;                             const bf16x8 qb = *(const LAS bf16x8*)(set + G2_QD + (16 * ti + fr) * 272 + ks * 64 + fq * 16);
;                             a4 = MFMA16(ka, qb, a4);
;                         }
;                         const int qi = 16 * ti + fr, kj = 16 * tj + 4 * fq;
;                         float m[4];
; #pragma unroll
;                         for (int e = 0; e < 4; ++e) { const bool keep = dir ? (kj + e > qi) : (kj + e <= qi); m[e] = keep ? a4[e] : 0.f; }
;                         u32x2 w; w.x = pk2(m[0], m[1]); w.y = pk2(m[2], m[3]);
;                         *(LAS u32x2*)(set + G2_SC + qi * 80 + kj * 2) = w;
;                     }
.LBB0_219:
	s_or_b64 exec, exec, s[6:7]
	s_mov_b32 s21, 0x5040100
	s_mov_b32 s24, 0x7060302
	v_add_u32_e32 v171, s15, v177
	s_waitcnt vmcnt(2)
	v_perm_b32 v16, v58, v54, s21
	v_perm_b32 v17, v66, v62, s21
	v_perm_b32 v18, v58, v54, s24
	v_perm_b32 v19, v66, v62, s24
	v_perm_b32 v20, v59, v55, s21
	v_perm_b32 v21, v67, v63, s21
	v_perm_b32 v22, v59, v55, s24
	v_perm_b32 v23, v67, v63, s24
	v_perm_b32 v24, v60, v56, s21
	v_perm_b32 v25, v68, v64, s21
	v_perm_b32 v26, v60, v56, s24
	v_perm_b32 v27, v68, v64, s24
	v_perm_b32 v28, v61, v57, s21
	v_perm_b32 v29, v69, v65, s21
	v_perm_b32 v30, v61, v57, s24
	v_perm_b32 v31, v69, v65, s24
	ds_write_b64 v171, v[16:17] offset:18944
	ds_write_b64 v171, v[18:19] offset:19024
	ds_write_b64 v171, v[20:21] offset:19104
	ds_write_b64 v171, v[22:23] offset:19184
	ds_write_b64 v171, v[24:25] offset:19264
	ds_write_b64 v171, v[26:27] offset:19344
	ds_write_b64 v171, v[28:29] offset:19424
	ds_write_b64 v171, v[30:31] offset:19504
	s_waitcnt lgkmcnt(0)
	s_barrier
	v_add3_u32 v28, s15, v207, v206
	ds_read_b128 v[134:137], v233
	ds_read_b128 v[138:141], v28
	ds_read_b128 v[142:145], v233 offset:64
	ds_read_b128 v[146:149], v28 offset:64
	ds_read_b128 v[150:153], v233 offset:128
	ds_read_b128 v[154:157], v28 offset:128
	ds_read_b128 v[162:165], v233 offset:192
	ds_read_b128 v[166:169], v28 offset:192
	s_add_i32 s20, s20, 1
	s_add_i32 s8, s8, -1
	s_waitcnt lgkmcnt(6)
	v_mfma_f32_16x16x32_bf16 v[16:19], v[134:137], v[138:141], 0
	s_waitcnt lgkmcnt(4)
	v_mfma_f32_16x16x32_bf16 v[16:19], v[142:145], v[146:149], v[16:19]
	s_waitcnt lgkmcnt(2)
	v_mfma_f32_16x16x32_bf16 v[16:19], v[150:153], v[154:157], v[16:19]
	s_cmp_eq_u32 s20, 64
	s_waitcnt lgkmcnt(0)
	v_mfma_f32_16x16x32_bf16 v[16:19], v[162:165], v[166:169], v[16:19]
	s_nop 7
	v_cndmask_b32_e64 v16, 0, v16, s[50:51]
	v_cndmask_b32_e64 v17, 0, v17, s[52:53]
	v_cndmask_b32_e64 v18, 0, v18, s[54:55]
	v_cndmask_b32_e64 v19, 0, v19, s[56:57]
	v_cvt_pk_bf16_f32 v16, v16, v17
	v_cvt_pk_bf16_f32 v17, v18, v19
	v_add3_u32 v18, s15, v208, v209
	ds_write_b64 v18, v[16:17] offset:39424
	s_waitcnt lgkmcnt(0)
	s_barrier
	s_cbranch_scc1 .LBB0_211
; #define LAS __attribute__((address_space(3)))
; __device__ __forceinline__ unsigned pk2(float lo, float hi) { f32x2 v = {lo, hi}; bf16x2_t b = __builtin_convertvector(v, bf16x2_t); return __builtin_bit_cast(unsigned, b); }
; __device__ __forceinline__ float bflo(unsigned w) { return __uint_as_float(w << 16); }
; __device__ __forceinline__ float bfhi(unsigned w) { return __uint_as_float(w & 0xffff0000u); }
; __device__ __forceinline__ void gla_scan_phase2(LAS unsigned char* lds, const bf16_t* proj, const float* gbuf, const float* wgu  , const float* bg  ,
;                                                 bf16_t* ob0, bf16_t* ob1) {
;     ...
;                     { const int n1 = n + 1 < NCH ? n + 1 : n; const float* grow = gbuf + (size_t)(b * SEQ + (dir ? NCH - 1 - n1 : n1) * CH + r) * 32 + dir * 16 + 8 * hh;
;                       gna = *(const f32x4*)grow; gnb = *(const f32x4*)(grow + 4); }
;                     {
;                         u32x4 ah, al;
;                         ah.x = pk2(ga[0], ga[1]); ah.y = pk2(ga[2], ga[3]); ah.z = pk2(gb[0], gb[1]); ah.w = pk2(gb[2], gb[3]);
;                         al.x = pk2(ga[0] - bflo(ah.x), ga[1] - bfhi(ah.x)); al.y = pk2(ga[2] - bflo(ah.y), ga[3] - bfhi(ah.y));
;                         al.z = pk2(gb[0] - bflo(ah.z), gb[1] - bfhi(ah.z)); al.w = pk2(gb[2] - bflo(ah.w), gb[3] - bfhi(ah.w));
;                         const bf16x8 gah = __builtin_bit_cast(bf16x8, ah), gal = __builtin_bit_cast(bf16x8, al);
;                         f32x16 zacc;
; #pragma unroll
;                         for (int i = 0; i < 16; ++i) zacc[i] = zbias;
;                         zacc = MFMA32(gah, wbh, zacc); zacc = MFMA32(gal, wbh, zacc); zacc = MFMA32(gah, wbl, zacc);
; #pragma unroll
;                         for (int i = 0; i < 16; ++i) *(LAS float*)(lds + G2_Z + (((i & 3) + 8 * (i >> 2) + 4 * hh) * 128 + 32 * zd + r) * 4) = zacc[i];
;                     }
;                     G2_BAR();
;                     float cs[16];
; #pragma unroll
;                     for (int ii = 0; ii < 16; ++ii) {
;                         const float z = *(const LAS float*)(lds + G2_Z + ((16 * seg + ii) * 128 + d) * 4);
;                         cs[ii] = fminf(z, 0.f) * (1.4426950408889634f / 16.f) - __builtin_amdgcn_logf(1.f + __builtin_amdgcn_exp2f(fabsf(z) * -1.4426950408889634f)) * (1.f / 16.f);
;                     }
.LBB0_220:
	s_waitcnt vmcnt(0)
	v_cvt_pk_bf16_f32 v102, v44, v45
	v_lshlrev_b32_e32 v16, 16, v102
	v_and_b32_e32 v17, 0xffff0000, v102
	v_cvt_pk_bf16_f32 v103, v46, v47
	v_cvt_pk_bf16_f32 v104, v40, v41
	v_cvt_pk_bf16_f32 v105, v42, v43
	v_pk_add_f32 v[16:17], v[44:45], v[16:17] neg_lo:[0,1] neg_hi:[0,1]
	s_and_b64 s[6:7], s[48:49], exec
	v_cvt_pk_bf16_f32 v44, v16, v17
	v_lshlrev_b32_e32 v16, 16, v103
	v_and_b32_e32 v17, 0xffff0000, v103
	v_pk_add_f32 v[16:17], v[46:47], v[16:17] neg_lo:[0,1] neg_hi:[0,1]
	s_cselect_b32 s0, s20, s8
	v_cvt_pk_bf16_f32 v45, v16, v17
	v_lshlrev_b32_e32 v16, 16, v104
	v_and_b32_e32 v17, 0xffff0000, v104
	v_pk_add_f32 v[16:17], v[40:41], v[16:17] neg_lo:[0,1] neg_hi:[0,1]
	v_lshlrev_b32_e32 v40, 16, v105
	v_cvt_pk_bf16_f32 v46, v16, v17
	v_mfma_f32_32x32x16_bf16 v[16:31], v[102:105], v[32:35], v[0:15]
	v_and_b32_e32 v41, 0xffff0000, v105
	v_add_f32_e64 v40, v42, -v40
	v_add_f32_e64 v41, v43, -v41
	s_lshl_b32 s0, s0, 5
	v_cvt_pk_bf16_f32 v47, v40, v41
	s_add_i32 s0, s0, s9
	s_mulk_i32 s0, 0x1a00
	s_or_b32 s6, s0, 0x1a00
	v_mfma_f32_32x32x16_bf16 v[16:31], v[44:47], v[32:35], v[16:31]
	s_or_b32 s7, s0, 0x3400
	s_add_i32 s15, s0, 0x4e00
	s_cmp_lt_u32 s20, 63
	buffer_load_dwordx4 v[54:57], v176, s[64:67], s0 offen
	buffer_load_dwordx4 v[58:61], v176, s[64:67], s6 offen
	buffer_load_dwordx4 v[62:65], v176, s[64:67], s7 offen
	buffer_load_dwordx4 v[66:69], v176, s[64:67], s15 offen
	s_cselect_b64 s[6:7], -1, 0
	s_cmp_lg_u64 s[6:7], 0
	s_addc_u32 s0, s20, 0
	s_cmp_lg_u64 s[6:7], 0
	s_subb_u32 s6, 0, 0
	v_mfma_f32_32x32x16_bf16 v[16:31], v[102:105], v[36:39], v[16:31]
	s_add_i32 s15, s8, s6
	s_and_b64 s[6:7], s[48:49], exec
	s_cselect_b32 s0, s0, s15
	v_lshl_add_u32 v40, s0, 5, v52
	v_ashrrev_i32_e32 v41, 31, v40
	v_lshlrev_b64 v[40:41], 7, v[40:41]
	v_lshl_add_u64 v[44:45], v[48:49], 0, v[40:41]
	global_load_dwordx4 v[40:43], v[44:45], off offset:16
	s_nop 0
	global_load_dwordx4 v[44:47], v[44:45], off
	s_nop 1
	ds_write_b32 v214, v16
	ds_write_b32 v215, v17
	ds_write_b32 v216, v18
	ds_write_b32 v217, v19
	ds_write_b32 v218, v20
	ds_write_b32 v219, v21
	ds_write_b32 v220, v22
	ds_write_b32 v221, v23
	ds_write_b32 v222, v24
	ds_write_b32 v223, v25
	ds_write_b32 v224, v26
	ds_write_b32 v225, v27
	ds_write_b32 v226, v28
	ds_write_b32 v227, v29
	ds_write_b32 v228, v30
	ds_write_b32 v229, v31
	s_waitcnt lgkmcnt(0)
	s_barrier
	ds_read2st64_b32 v[118:119], v230 offset1:2
	ds_read2st64_b32 v[120:121], v230 offset0:4 offset1:6
	ds_read2st64_b32 v[122:123], v230 offset0:8 offset1:10
	ds_read2st64_b32 v[124:125], v230 offset0:12 offset1:14
	ds_read2st64_b32 v[126:127], v230 offset0:16 offset1:18
	ds_read2st64_b32 v[128:129], v230 offset0:20 offset1:22
	ds_read2st64_b32 v[130:131], v230 offset0:24 offset1:26
	ds_read2st64_b32 v[132:133], v230 offset0:28 offset1:30
	s_andn2_b64 vcc, exec, s[68:69]
	s_mov_b64 s[6:7], -1
	s_waitcnt lgkmcnt(4)
	v_mul_f32_e64 v134, |v118|, s1
	v_mul_f32_e64 v135, |v119|, s1
	v_mul_f32_e64 v136, |v120|, s1
	v_mul_f32_e64 v137, |v121|, s1
	v_mul_f32_e64 v138, |v122|, s1
	v_mul_f32_e64 v139, |v123|, s1
	v_mul_f32_e64 v140, |v124|, s1
	v_mul_f32_e64 v141, |v125|, s1
	s_waitcnt lgkmcnt(0)
	v_mul_f32_e64 v142, |v126|, s1
	v_mul_f32_e64 v143, |v127|, s1
	v_mul_f32_e64 v144, |v128|, s1
	v_mul_f32_e64 v145, |v129|, s1
	v_mul_f32_e64 v146, |v130|, s1
	v_mul_f32_e64 v147, |v131|, s1
	v_mul_f32_e64 v148, |v132|, s1
	v_mul_f32_e64 v149, |v133|, s1
	v_exp_f32_e32 v134, v134
	v_exp_f32_e32 v135, v135
	v_exp_f32_e32 v136, v136
	v_exp_f32_e32 v137, v137
	v_exp_f32_e32 v138, v138
	v_exp_f32_e32 v139, v139
	v_exp_f32_e32 v140, v140
	v_exp_f32_e32 v141, v141
	v_exp_f32_e32 v142, v142
	v_exp_f32_e32 v143, v143
	v_exp_f32_e32 v144, v144
	v_exp_f32_e32 v145, v145
	v_exp_f32_e32 v146, v146
	v_exp_f32_e32 v147, v147
	v_exp_f32_e32 v148, v148
	v_exp_f32_e32 v149, v149
	v_min_f32_e32 v118, 0, v118
	v_min_f32_e32 v119, 0, v119
	v_min_f32_e32 v120, 0, v120
	v_min_f32_e32 v121, 0, v121
	v_min_f32_e32 v122, 0, v122
	v_min_f32_e32 v123, 0, v123
	v_min_f32_e32 v124, 0, v124
	v_min_f32_e32 v125, 0, v125
	v_min_f32_e32 v126, 0, v126
	v_min_f32_e32 v127, 0, v127
	v_min_f32_e32 v128, 0, v128
	v_min_f32_e32 v129, 0, v129
	v_min_f32_e32 v130, 0, v130
	v_min_f32_e32 v131, 0, v131
	v_min_f32_e32 v132, 0, v132
	v_min_f32_e32 v133, 0, v133
	v_add_f32_e32 v134, 1.0, v134
	v_add_f32_e32 v135, 1.0, v135
	v_add_f32_e32 v136, 1.0, v136
	v_add_f32_e32 v137, 1.0, v137
	v_add_f32_e32 v138, 1.0, v138
	v_add_f32_e32 v139, 1.0, v139
	v_add_f32_e32 v140, 1.0, v140
	v_add_f32_e32 v141, 1.0, v141
	v_add_f32_e32 v142, 1.0, v142
	v_add_f32_e32 v143, 1.0, v143
	v_add_f32_e32 v144, 1.0, v144
	v_add_f32_e32 v145, 1.0, v145
	v_add_f32_e32 v146, 1.0, v146
	v_add_f32_e32 v147, 1.0, v147
	v_add_f32_e32 v148, 1.0, v148
	v_add_f32_e32 v149, 1.0, v149
	v_log_f32_e32 v134, v134
	v_log_f32_e32 v135, v135
	v_log_f32_e32 v136, v136
	v_log_f32_e32 v137, v137
	v_log_f32_e32 v138, v138
	v_log_f32_e32 v139, v139
	v_log_f32_e32 v140, v140
	v_log_f32_e32 v141, v141
	v_log_f32_e32 v142, v142
	v_log_f32_e32 v143, v143
	v_log_f32_e32 v144, v144
	v_log_f32_e32 v145, v145
	v_log_f32_e32 v146, v146
	v_log_f32_e32 v147, v147
	v_log_f32_e32 v148, v148
	v_log_f32_e32 v149, v149
	v_mul_f32_e32 v134, 0x3d800000, v134
	v_mul_f32_e32 v135, 0x3d800000, v135
	v_mul_f32_e32 v136, 0x3d800000, v136
	v_mul_f32_e32 v137, 0x3d800000, v137
	v_mul_f32_e32 v138, 0x3d800000, v138
	v_mul_f32_e32 v139, 0x3d800000, v139
	v_mul_f32_e32 v140, 0x3d800000, v140
	v_mul_f32_e32 v141, 0x3d800000, v141
	v_mul_f32_e32 v142, 0x3d800000, v142
	v_mul_f32_e32 v143, 0x3d800000, v143
	v_mul_f32_e32 v144, 0x3d800000, v144
	v_mul_f32_e32 v145, 0x3d800000, v145
	v_mul_f32_e32 v146, 0x3d800000, v146
	v_mul_f32_e32 v147, 0x3d800000, v147
	v_mul_f32_e32 v148, 0x3d800000, v148
	v_mul_f32_e32 v149, 0x3d800000, v149
	v_fma_f32 v16, v118, s10, -v134
	v_fma_f32 v25, v119, s10, -v135
	v_fma_f32 v26, v120, s10, -v136
	v_fma_f32 v29, v121, s10, -v137
	v_fma_f32 v30, v122, s10, -v138
	v_fma_f32 v102, v123, s10, -v139
	v_fma_f32 v104, v124, s10, -v140
	v_fma_f32 v105, v125, s10, -v141
	v_fma_f32 v108, v126, s10, -v142
	v_fma_f32 v109, v127, s10, -v143
	v_fma_f32 v111, v128, s10, -v144
	v_fma_f32 v112, v129, s10, -v145
	v_fma_f32 v113, v130, s10, -v146
	v_fma_f32 v114, v131, s10, -v147
	v_fma_f32 v116, v132, s10, -v148
	v_fma_f32 v17, v133, s10, -v149
	s_cbranch_vccnz .LBB0_222
	v_add_f32_e32 v18, v116, v17
	v_add_f32_e32 v19, v114, v18
	v_add_f32_e32 v20, v113, v19
	v_add_f32_e32 v21, v112, v20
	v_add_f32_e32 v22, v111, v21
	v_add_f32_e32 v23, v109, v22
	v_add_f32_e32 v24, v108, v23
	v_add_f32_e32 v27, v105, v24
	v_add_f32_e32 v28, v104, v27
	v_add_f32_e32 v31, v102, v28
	v_add_f32_e32 v103, v30, v31
	v_add_f32_e32 v106, v29, v103
	v_add_f32_e32 v107, v26, v106
	v_add_f32_e32 v110, v25, v107
	v_add_f32_e32 v115, v16, v110
	s_mov_b64 s[6:7], 0
